# diff attention: first-QK reference fill uses 64-bit moves and a two-way branch instead of the four-way flag diamond; MLA row-max hazard distance restored after dropping priority flips
# speedup vs baseline: 1.0126x; 1.0075x over previous
.LBB0_233:
	ds_read_b128 v[174:177], v254 offset:12288
	ds_read_b128 v[186:189], v254 offset:12800
	ds_read_b128 v[182:185], v254 offset:14336
	ds_read_b128 v[178:181], v254 offset:14848
	v_lshl_add_u64 v[226:227], v[218:219], 0, s[12:13]
	v_add_co_u32_e32 v114, vcc, 0x9700000, v226
	s_waitcnt vmcnt(1)
	ds_write_b128 v217, v[162:165]
	ds_write_b128 v217, v[166:169] offset:40960
	s_waitcnt vmcnt(0)
	ds_write_b128 v217, v[170:173] offset:49152
	v_addc_co_u32_e32 v115, vcc, 0, v227, vcc
	global_load_dwordx4 v[162:165], v[114:115], off offset:1024
	v_lshl_add_u64 v[114:115], v[222:223], 0, s[12:13]
	v_add_co_u32_e32 v114, vcc, 0x9400000, v114
	s_nop 1
	v_addc_co_u32_e32 v115, vcc, 0, v115, vcc
	global_load_dwordx4 v[170:173], v[114:115], off offset:2048
	global_load_dwordx4 v[166:169], v[114:115], off offset:2176
	v_cmp_eq_f32_e32 vcc, 0, v236
	s_cmp_eq_u64 vcc, exec
	s_cbranch_scc1 .Lfz_A
	v_xor_b32_e32 v130, 0x80000000, v236
	v_mov_b32_e32 v131, v130
	v_mov_b64_e32 v[132:133], v[130:131]
	v_mov_b64_e32 v[134:135], v[130:131]
	v_mov_b64_e32 v[136:137], v[130:131]
	v_mov_b64_e32 v[138:139], v[130:131]
	v_mov_b64_e32 v[140:141], v[130:131]
	v_mov_b64_e32 v[142:143], v[130:131]
	v_mov_b64_e32 v[144:145], v[130:131]
	v_exp_f32_e32 v98, v98
	v_exp_f32_e32 v99, v99
	s_waitcnt lgkmcnt(6)
	v_mfma_f32_32x32x16_bf16 v[114:129], v[174:177], v[158:161], v[130:145]
	v_add_f32_e32 v224, v224, v98
	v_cvt_pk_bf16_f32 v174, v98, v99
	v_add_f32_e32 v225, v225, v99
	s_waitcnt lgkmcnt(5)
	v_mfma_f32_32x32x16_bf16 v[82:97], v[186:189], v[158:161], v[130:145]

.LBB0_247:
	v_lshl_add_u64 v[98:99], v[220:221], 0, s[12:13]
	v_add_co_u32_e32 v98, vcc, 0x9400000, v98
	s_nop 1
	v_addc_co_u32_e32 v99, vcc, 0, v99, vcc
	global_load_dwordx4 v[166:169], v[98:99], off offset:2048
	global_load_dwordx4 v[170:173], v[98:99], off offset:2176
	v_cmp_eq_f32_e32 vcc, 0, v236
	s_cmp_eq_u64 vcc, exec
	s_cbranch_scc1 .Lfz_B
	v_xor_b32_e32 v130, 0x80000000, v236
	v_mov_b32_e32 v131, v130
	v_mov_b64_e32 v[132:133], v[130:131]
	v_mov_b64_e32 v[134:135], v[130:131]
	v_mov_b64_e32 v[136:137], v[130:131]
	v_mov_b64_e32 v[138:139], v[130:131]
	v_mov_b64_e32 v[140:141], v[130:131]
	v_mov_b64_e32 v[142:143], v[130:131]
	v_mov_b64_e32 v[144:145], v[130:131]
	v_exp_f32_e32 v114, v114
	v_exp_f32_e32 v115, v115
	s_waitcnt lgkmcnt(6)
	v_mfma_f32_32x32x16_bf16 v[98:113], v[174:177], v[158:161], v[130:145]
	v_add_f32_e32 v224, v224, v114
	v_cvt_pk_bf16_f32 v174, v114, v115
	v_add_f32_e32 v225, v225, v115
	s_waitcnt lgkmcnt(5)
	v_mfma_f32_32x32x16_bf16 v[66:81], v[186:189], v[158:161], v[130:145]
	s_branch .LBB0_228

.Lfz_A:
	v_exp_f32_e32 v98, v98
	v_exp_f32_e32 v99, v99
	s_waitcnt lgkmcnt(6)
	v_mfma_f32_32x32x16_bf16 v[114:129], v[174:177], v[158:161], 0
	v_add_f32_e32 v224, v224, v98
	v_cvt_pk_bf16_f32 v174, v98, v99
	v_add_f32_e32 v225, v225, v99
	s_waitcnt lgkmcnt(5)
	v_mfma_f32_32x32x16_bf16 v[82:97], v[186:189], v[158:161], 0
	s_branch .LBB0_241
.Lfz_B:
	v_exp_f32_e32 v114, v114
	v_exp_f32_e32 v115, v115
	s_waitcnt lgkmcnt(6)
	v_mfma_f32_32x32x16_bf16 v[98:113], v[174:177], v[158:161], 0
	v_add_f32_e32 v224, v224, v114
	v_cvt_pk_bf16_f32 v174, v114, v115
	v_add_f32_e32 v225, v225, v115
	s_waitcnt lgkmcnt(5)
	v_mfma_f32_32x32x16_bf16 v[66:81], v[186:189], v[158:161], 0
	s_branch .LBB0_228

.LBB0_287:
	v_lshl_add_u64 v[50:51], s[80:81], 0, v[222:223]
	global_load_dwordx4 v[178:181], v[50:51], off
	s_waitcnt lgkmcnt(3)
	v_mfma_f32_32x32x16_bf16 v[50:65], v[68:71], v[166:169], v[34:49]
	v_exp_f32_e32 v72, v114
	v_exp_f32_e32 v73, v115
	ds_read_b128 v[90:93], v254 offset:2048
	ds_read_b128 v[94:97], v254 offset:2560
	v_exp_f32_e32 v74, v130
	v_exp_f32_e32 v75, v131
	v_pk_add_f32 v[66:67], v[66:67], v[72:73]
	v_cvt_pk_bf16_f32 v114, v72, v73
	v_cvt_pk_bf16_f32 v84, v74, v75
	s_nop 0
	v_pk_add_f32 v[130:131], v[74:75], v[66:67]
	s_waitcnt lgkmcnt(4)
	v_mfma_f32_32x32x16_bf16 v[66:81], v[86:89], v[166:169], v[34:49]
	v_exp_f32_e32 v86, v116
	v_exp_f32_e32 v87, v117
	v_exp_f32_e32 v88, v132
	v_exp_f32_e32 v89, v133
	v_cvt_pk_bf16_f32 v115, v86, v87
	v_pk_add_f32 v[116:117], v[86:87], v[130:131]
	v_cvt_pk_bf16_f32 v85, v88, v89
	s_nop 0
	v_pk_add_f32 v[116:117], v[88:89], v[116:117]
	s_waitcnt lgkmcnt(1)
	v_mfma_f32_32x32x16_bf16 v[50:65], v[90:93], v[162:165], v[50:65]
	ds_read_b128 v[130:133], v254 offset:4096
	ds_read_b128 v[190:193], v254 offset:4608
	v_exp_f32_e32 v86, v118
	v_exp_f32_e32 v87, v119
	v_exp_f32_e32 v88, v134
	v_exp_f32_e32 v89, v135
	v_pk_add_f32 v[90:91], v[86:87], v[116:117]
	v_cvt_pk_bf16_f32 v116, v86, v87
	s_nop 0
	v_pk_add_f32 v[90:91], v[88:89], v[90:91]
	v_cvt_pk_bf16_f32 v86, v88, v89
	s_waitcnt lgkmcnt(2)
	v_mfma_f32_32x32x16_bf16 v[66:81], v[94:97], v[162:165], v[66:81]
	v_exp_f32_e32 v88, v120
	v_exp_f32_e32 v89, v121
	v_exp_f32_e32 v92, v136
	v_exp_f32_e32 v93, v137
	v_cvt_pk_bf16_f32 v117, v88, v89
	v_pk_add_f32 v[90:91], v[88:89], v[90:91]
	v_cvt_pk_bf16_f32 v87, v92, v93
	s_nop 0
	v_pk_add_f32 v[96:97], v[92:93], v[90:91]
	s_waitcnt lgkmcnt(1)
	v_mfma_f32_32x32x16_bf16 v[50:65], v[130:133], v[158:161], v[50:65]
	ds_read_b128 v[88:91], v254 offset:6144
	ds_read_b128 v[92:95], v254 offset:6656
	v_exp_f32_e32 v118, v122
	v_exp_f32_e32 v119, v123
	v_exp_f32_e32 v120, v138
	v_exp_f32_e32 v121, v139
	v_pk_add_f32 v[96:97], v[118:119], v[96:97]
	v_cvt_pk_bf16_f32 v118, v118, v119
	s_nop 0
	v_pk_add_f32 v[96:97], v[120:121], v[96:97]
	v_cvt_pk_bf16_f32 v122, v120, v121
	s_waitcnt lgkmcnt(2)
	v_mfma_f32_32x32x16_bf16 v[66:81], v[190:193], v[158:161], v[66:81]
	v_exp_f32_e32 v120, v124
	v_exp_f32_e32 v121, v125
	v_exp_f32_e32 v124, v140
	v_exp_f32_e32 v125, v141
	v_cvt_pk_bf16_f32 v119, v120, v121
	v_pk_add_f32 v[96:97], v[120:121], v[96:97]
	v_cvt_pk_bf16_f32 v123, v124, v125
	s_nop 0
	v_pk_add_f32 v[96:97], v[124:125], v[96:97]
	s_waitcnt lgkmcnt(1)
	v_mfma_f32_32x32x16_bf16 v[50:65], v[88:91], v[154:157], v[50:65]
	ds_read_b128 v[132:135], v254 offset:8192
	ds_read_b128 v[136:139], v254 offset:8704
	v_exp_f32_e32 v88, v126
	v_exp_f32_e32 v89, v127
	v_exp_f32_e32 v90, v142
	v_exp_f32_e32 v91, v143
	v_cvt_pk_bf16_f32 v120, v88, v89
	v_pk_add_f32 v[96:97], v[88:89], v[96:97]
	v_cvt_pk_bf16_f32 v124, v90, v91
	s_nop 0
	v_pk_add_f32 v[96:97], v[90:91], v[96:97]
	s_waitcnt lgkmcnt(2)
	v_mfma_f32_32x32x16_bf16 v[66:81], v[92:95], v[154:157], v[66:81]
	v_exp_f32_e32 v88, v128
	v_exp_f32_e32 v89, v129
	v_exp_f32_e32 v90, v144
	v_exp_f32_e32 v91, v145
	v_cvt_pk_bf16_f32 v121, v88, v89
	v_pk_add_f32 v[92:93], v[88:89], v[96:97]
	v_cvt_pk_bf16_f32 v125, v90, v91
	s_nop 0
	v_pk_add_f32 v[130:131], v[90:91], v[92:93]
	s_waitcnt lgkmcnt(1)
	v_mfma_f32_32x32x16_bf16 v[50:65], v[132:135], v[150:153], v[50:65]
	ds_read_b128 v[88:91], v254 offset:10240
	ds_read_b128 v[92:95], v254 offset:10752
	s_waitcnt lgkmcnt(2)
	v_mfma_f32_32x32x16_bf16 v[66:81], v[136:139], v[150:153], v[66:81]
	s_waitcnt lgkmcnt(1)
	v_mfma_f32_32x32x16_bf16 v[50:65], v[88:91], v[146:149], v[50:65]
	s_waitcnt lgkmcnt(0)
	v_mfma_f32_32x32x16_bf16 v[66:81], v[92:95], v[146:149], v[66:81]
	ds_read_b64_tr_b16 v[88:89], v243 offset:40960
	ds_read_b64_tr_b16 v[90:91], v243 offset:41472
	ds_read_b64_tr_b16 v[92:93], v243 offset:45056
	ds_read_b64_tr_b16 v[94:95], v243 offset:45568
	s_waitcnt lgkmcnt(2)
	v_mfma_f32_32x32x16_bf16 v[18:33], v[114:117], v[88:91], v[18:33]
	ds_read_b64_tr_b16 v[126:127], v243 offset:41984
	ds_read_b64_tr_b16 v[128:129], v243 offset:42496
	s_nop 1
	v_max_f32_e32 v83, v50, v50
	v_max_f32_e32 v83, 0xf149f2ca, v83
	v_max3_f32 v96, v66, s25, v67
	s_waitcnt lgkmcnt(2)
	v_mfma_f32_32x32x16_bf16 v[2:17], v[114:117], v[92:95], v[2:17]
	ds_read_b64_tr_b16 v[88:89], v243 offset:46080
	ds_read_b64_tr_b16 v[90:91], v243 offset:46592
	v_max3_f32 v83, v83, v51, v52
	v_max3_f32 v96, v96, v68, v69
	s_waitcnt lgkmcnt(2)
	v_mfma_f32_32x32x16_bf16 v[18:33], v[118:121], v[126:129], v[18:33]
	ds_read_b64_tr_b16 v[92:93], v243 offset:43008
	ds_read_b64_tr_b16 v[94:95], v243 offset:43520
	v_max3_f32 v83, v83, v53, v54
	v_max3_f32 v96, v96, v70, v71
	s_waitcnt lgkmcnt(2)
	v_mfma_f32_32x32x16_bf16 v[2:17], v[118:121], v[88:91], v[2:17]
	ds_read_b64_tr_b16 v[114:115], v243 offset:47104
	ds_read_b64_tr_b16 v[116:117], v243 offset:47616
	v_max3_f32 v83, v83, v55, v56
	v_max3_f32 v96, v96, v72, v73
	s_waitcnt lgkmcnt(2)
	v_mfma_f32_32x32x16_bf16 v[18:33], v[84:87], v[92:95], v[18:33]
	ds_read_b64_tr_b16 v[88:89], v243 offset:44032
	ds_read_b64_tr_b16 v[90:91], v243 offset:44544
	v_max3_f32 v83, v83, v57, v58
	v_max3_f32 v96, v96, v74, v75
	s_waitcnt lgkmcnt(2)
	v_mfma_f32_32x32x16_bf16 v[2:17], v[84:87], v[114:117], v[2:17]
	ds_read_b64_tr_b16 v[92:93], v243 offset:48128
	ds_read_b64_tr_b16 v[94:95], v243 offset:48640
	s_waitcnt lgkmcnt(2)
	v_mfma_f32_32x32x16_bf16 v[18:33], v[122:125], v[88:91], v[18:33]
	s_waitcnt lgkmcnt(0)
	v_mfma_f32_32x32x16_bf16 v[2:17], v[122:125], v[92:95], v[2:17]
	v_max3_f32 v83, v83, v59, v60
	v_max3_f32 v84, v96, v76, v77
	v_max3_f32 v83, v83, v61, v62
	v_max3_f32 v84, v84, v78, v79
	v_max3_f32 v83, v83, v63, v64
	v_max3_f32 v84, v84, v80, v81
	s_add_i32 s36, s36, 2
	v_max3_f32 v83, v83, v65, v84
	v_lshl_add_u64 v[218:219], v[218:219], 0, s[38:39]
	v_lshl_add_u64 v[220:221], v[220:221], 0, s[82:83]
	v_lshl_add_u64 v[222:223], v[222:223], 0, s[82:83]
	s_cmpk_gt_u32 s36, 0x7d
	v_lshl_add_u64 v[224:225], v[224:225], 0, s[82:83]
	s_barrier
	s_cbranch_scc1 .LBB0_305

.LBB0_295:
	v_lshl_add_u64 v[114:115], s[80:81], 0, v[224:225]
	global_load_dwordx4 v[178:181], v[114:115], off
	s_waitcnt lgkmcnt(3)
	v_mfma_f32_32x32x16_bf16 v[114:129], v[84:87], v[166:169], v[34:49]
	ds_read_b128 v[92:95], v254 offset:14336
	ds_read_b128 v[190:193], v254 offset:14848
	v_exp_f32_e32 v50, v50
	v_exp_f32_e32 v51, v51
	v_exp_f32_e32 v66, v66
	v_exp_f32_e32 v67, v67
	v_pk_add_f32 v[84:85], v[130:131], v[50:51]
	s_nop 0
	v_pk_add_f32 v[86:87], v[66:67], v[84:85]
	v_cvt_pk_bf16_f32 v84, v50, v51
	v_cvt_pk_bf16_f32 v50, v66, v67
	s_waitcnt lgkmcnt(4)
	v_mfma_f32_32x32x16_bf16 v[130:145], v[88:91], v[166:169], v[34:49]
	v_exp_f32_e32 v52, v52
	v_exp_f32_e32 v53, v53
	v_exp_f32_e32 v66, v68
	v_exp_f32_e32 v67, v69
	v_cvt_pk_bf16_f32 v85, v52, v53
	v_pk_add_f32 v[68:69], v[52:53], v[86:87]
	v_cvt_pk_bf16_f32 v51, v66, v67
	s_nop 0
	v_pk_add_f32 v[86:87], v[66:67], v[68:69]
	s_waitcnt lgkmcnt(1)
	v_mfma_f32_32x32x16_bf16 v[114:129], v[92:95], v[162:165], v[114:129]
	ds_read_b128 v[66:69], v254 offset:16384
	ds_read_b128 v[88:91], v254 offset:16896
	v_exp_f32_e32 v52, v54
	v_exp_f32_e32 v53, v55
	v_exp_f32_e32 v54, v70
	v_exp_f32_e32 v55, v71
	v_pk_add_f32 v[70:71], v[52:53], v[86:87]
	v_cvt_pk_bf16_f32 v86, v52, v53
	s_nop 0
	v_pk_add_f32 v[70:71], v[54:55], v[70:71]
	v_cvt_pk_bf16_f32 v52, v54, v55
	s_waitcnt lgkmcnt(2)
	v_mfma_f32_32x32x16_bf16 v[130:145], v[190:193], v[162:165], v[130:145]
	v_exp_f32_e32 v54, v56
	v_exp_f32_e32 v55, v57
	v_exp_f32_e32 v56, v72
	v_exp_f32_e32 v57, v73
	v_cvt_pk_bf16_f32 v87, v54, v55
	v_pk_add_f32 v[70:71], v[54:55], v[70:71]
	v_cvt_pk_bf16_f32 v53, v56, v57
	s_nop 0
	v_pk_add_f32 v[92:93], v[56:57], v[70:71]
	s_waitcnt lgkmcnt(1)
	v_mfma_f32_32x32x16_bf16 v[114:129], v[66:69], v[158:161], v[114:129]
	ds_read_b128 v[54:57], v254 offset:18432
	ds_read_b128 v[70:73], v254 offset:18944
	v_exp_f32_e32 v58, v58
	v_exp_f32_e32 v59, v59
	v_exp_f32_e32 v66, v74
	v_exp_f32_e32 v67, v75
	v_pk_add_f32 v[68:69], v[58:59], v[92:93]
	v_cvt_pk_bf16_f32 v58, v58, v59
	s_nop 0
	v_pk_add_f32 v[68:69], v[66:67], v[68:69]
	v_cvt_pk_bf16_f32 v74, v66, v67
	s_waitcnt lgkmcnt(2)
	v_mfma_f32_32x32x16_bf16 v[130:145], v[88:91], v[158:161], v[130:145]
	v_exp_f32_e32 v60, v60
	v_exp_f32_e32 v61, v61
	v_exp_f32_e32 v66, v76
	v_exp_f32_e32 v67, v77
	v_cvt_pk_bf16_f32 v59, v60, v61
	v_pk_add_f32 v[68:69], v[60:61], v[68:69]
	v_cvt_pk_bf16_f32 v75, v66, v67
	s_nop 0
	v_pk_add_f32 v[68:69], v[66:67], v[68:69]
	s_waitcnt lgkmcnt(1)
	v_mfma_f32_32x32x16_bf16 v[114:129], v[54:57], v[154:157], v[114:129]
	ds_read_b128 v[88:91], v254 offset:20480
	ds_read_b128 v[92:95], v254 offset:20992
	v_exp_f32_e32 v54, v62
	v_exp_f32_e32 v55, v63
	v_exp_f32_e32 v56, v78
	v_exp_f32_e32 v57, v79
	v_pk_add_f32 v[60:61], v[54:55], v[68:69]
	s_nop 0
	v_pk_add_f32 v[62:63], v[56:57], v[60:61]
	v_cvt_pk_bf16_f32 v60, v54, v55
	v_cvt_pk_bf16_f32 v76, v56, v57
	s_waitcnt lgkmcnt(2)
	v_mfma_f32_32x32x16_bf16 v[130:145], v[70:73], v[154:157], v[130:145]
	v_exp_f32_e32 v54, v64
	v_exp_f32_e32 v55, v65
	v_exp_f32_e32 v56, v80
	v_exp_f32_e32 v57, v81
	v_cvt_pk_bf16_f32 v61, v54, v55
	v_pk_add_f32 v[62:63], v[54:55], v[62:63]
	v_cvt_pk_bf16_f32 v77, v56, v57
	s_nop 0
	v_pk_add_f32 v[66:67], v[56:57], v[62:63]
	s_waitcnt lgkmcnt(1)
	v_mfma_f32_32x32x16_bf16 v[114:129], v[88:91], v[150:153], v[114:129]
	ds_read_b128 v[54:57], v254 offset:22528
	ds_read_b128 v[62:65], v254 offset:23040
	s_waitcnt lgkmcnt(2)
	v_mfma_f32_32x32x16_bf16 v[130:145], v[92:95], v[150:153], v[130:145]
	s_waitcnt lgkmcnt(1)
	v_mfma_f32_32x32x16_bf16 v[114:129], v[54:57], v[146:149], v[114:129]
	s_waitcnt lgkmcnt(0)
	v_mfma_f32_32x32x16_bf16 v[130:145], v[62:65], v[146:149], v[130:145]
	ds_read_b64_tr_b16 v[54:55], v243 offset:24576
	ds_read_b64_tr_b16 v[56:57], v243 offset:25088
	ds_read_b64_tr_b16 v[62:63], v243 offset:28672
	ds_read_b64_tr_b16 v[64:65], v243 offset:29184
	s_waitcnt lgkmcnt(2)
	v_mfma_f32_32x32x16_bf16 v[18:33], v[84:87], v[54:57], v[18:33]
	ds_read_b64_tr_b16 v[68:69], v243 offset:25600
	ds_read_b64_tr_b16 v[70:71], v243 offset:26112
	s_nop 1
	v_max_f32_e32 v54, v114, v114
	v_max_f32_e32 v72, 0xf149f2ca, v54
	v_max3_f32 v73, v130, s25, v131
	s_waitcnt lgkmcnt(2)
	v_mfma_f32_32x32x16_bf16 v[2:17], v[84:87], v[62:65], v[2:17]
	ds_read_b64_tr_b16 v[54:55], v243 offset:29696
	ds_read_b64_tr_b16 v[56:57], v243 offset:30208
	v_max3_f32 v72, v72, v115, v116
	v_max3_f32 v73, v73, v132, v133
	s_waitcnt lgkmcnt(2)
	v_mfma_f32_32x32x16_bf16 v[18:33], v[58:61], v[68:71], v[18:33]
	ds_read_b64_tr_b16 v[62:63], v243 offset:26624
	ds_read_b64_tr_b16 v[64:65], v243 offset:27136
	v_max3_f32 v72, v72, v117, v118
	v_max3_f32 v73, v73, v134, v135
	s_waitcnt lgkmcnt(2)
	v_mfma_f32_32x32x16_bf16 v[2:17], v[58:61], v[54:57], v[2:17]
	ds_read_b64_tr_b16 v[68:69], v243 offset:30720
	ds_read_b64_tr_b16 v[70:71], v243 offset:31232
	v_max3_f32 v58, v72, v119, v120
	v_max3_f32 v59, v73, v136, v137
	s_waitcnt lgkmcnt(2)
	v_mfma_f32_32x32x16_bf16 v[18:33], v[50:53], v[62:65], v[18:33]
	ds_read_b64_tr_b16 v[54:55], v243 offset:27648
	ds_read_b64_tr_b16 v[56:57], v243 offset:28160
	v_max3_f32 v62, v58, v121, v122
	v_max3_f32 v63, v59, v138, v139
	s_waitcnt lgkmcnt(2)
	v_mfma_f32_32x32x16_bf16 v[2:17], v[50:53], v[68:71], v[2:17]
	ds_read_b64_tr_b16 v[58:59], v243 offset:31744
	ds_read_b64_tr_b16 v[60:61], v243 offset:32256
	s_waitcnt lgkmcnt(2)
	v_mfma_f32_32x32x16_bf16 v[18:33], v[74:77], v[54:57], v[18:33]
	s_waitcnt lgkmcnt(0)
	v_mfma_f32_32x32x16_bf16 v[2:17], v[74:77], v[58:61], v[2:17]
	v_max3_f32 v50, v63, v140, v141
	v_max3_f32 v50, v50, v142, v143
	v_max3_f32 v51, v62, v123, v124
	v_max3_f32 v51, v51, v125, v126
	v_max3_f32 v50, v50, v144, v145
	v_max3_f32 v51, v51, v127, v128
	v_max3_f32 v50, v51, v129, v50
	v_cmp_lt_f32_e32 vcc, s16, v50
	s_barrier
	s_cbranch_vccz .LBB0_299
	ds_bpermute_b32 v34, v251, v50
	s_waitcnt lgkmcnt(0)
	v_max3_f32 v35, v50, v34, 0
	v_exp_f32_e64 v34, -v35
	s_and_saveexec_b64 s[12:13], s[6:7]
	ds_write_b32 v209, v34 offset:57344
	s_or_b64 exec, exec, s[12:13]
	ds_read_b128 v[36:39], v207 offset:57408
	ds_read_b128 v[40:43], v207 offset:57440
	ds_read_b128 v[44:47], v207 offset:57344
	ds_read_b128 v[48:51], v207 offset:57376
	v_add_f32_e32 v229, v229, v35
	v_xor_b32_e32 v82, 0x80000000, v229
	v_mov_b32_e32 v83, v82
	v_sub_f32_e32 v129, v129, v35
	v_sub_f32_e32 v128, v128, v35
	v_sub_f32_e32 v127, v127, v35
	v_sub_f32_e32 v126, v126, v35
	v_sub_f32_e32 v125, v125, v35
	v_sub_f32_e32 v124, v124, v35
	v_sub_f32_e32 v123, v123, v35
	v_sub_f32_e32 v122, v122, v35
	v_sub_f32_e32 v121, v121, v35
	v_sub_f32_e32 v120, v120, v35
	v_sub_f32_e32 v119, v119, v35
	v_sub_f32_e32 v118, v118, v35
	v_sub_f32_e32 v117, v117, v35
	v_sub_f32_e32 v116, v116, v35
	v_sub_f32_e32 v115, v115, v35
	v_sub_f32_e32 v114, v114, v35
	v_sub_f32_e32 v145, v145, v35
	v_sub_f32_e32 v144, v144, v35
	v_sub_f32_e32 v143, v143, v35
	v_sub_f32_e32 v142, v142, v35
	v_sub_f32_e32 v141, v141, v35
	v_sub_f32_e32 v140, v140, v35
	v_sub_f32_e32 v139, v139, v35
	v_sub_f32_e32 v138, v138, v35
	v_sub_f32_e32 v137, v137, v35
	v_sub_f32_e32 v136, v136, v35
	v_sub_f32_e32 v135, v135, v35
	v_sub_f32_e32 v134, v134, v35
	v_sub_f32_e32 v133, v133, v35
	v_sub_f32_e32 v132, v132, v35
	v_sub_f32_e32 v131, v131, v35
	v_sub_f32_e32 v130, v130, v35
	v_pk_mul_f32 v[66:67], v[66:67], v[34:35] op_sel_hi:[1,0]
	s_waitcnt lgkmcnt(2)
	v_pk_mul_f32 v[32:33], v[32:33], v[42:43]
	v_pk_mul_f32 v[28:29], v[28:29], v[38:39]
	s_waitcnt lgkmcnt(1)
	v_pk_mul_f32 v[20:21], v[20:21], v[46:47]
	v_pk_mul_f32 v[30:31], v[30:31], v[40:41]
	v_pk_mul_f32 v[26:27], v[26:27], v[36:37]
	s_waitcnt lgkmcnt(0)
	v_pk_mul_f32 v[22:23], v[22:23], v[48:49]
	v_pk_mul_f32 v[18:19], v[18:19], v[44:45]
	v_pk_mul_f32 v[16:17], v[16:17], v[42:43]
	v_pk_mul_f32 v[12:13], v[12:13], v[38:39]
	v_pk_mul_f32 v[4:5], v[4:5], v[46:47]
	v_pk_mul_f32 v[14:15], v[14:15], v[40:41]
	v_pk_mul_f32 v[10:11], v[10:11], v[36:37]
	v_pk_mul_f32 v[6:7], v[6:7], v[48:49]
	v_pk_mul_f32 v[2:3], v[2:3], v[44:45]
	v_mov_b32_e32 v84, v82
	v_mov_b32_e32 v85, v82
	v_mov_b32_e32 v86, v82
	v_mov_b32_e32 v87, v82
	v_mov_b32_e32 v88, v82
	v_mov_b32_e32 v89, v82
	v_mov_b32_e32 v90, v82
	v_mov_b32_e32 v91, v82
	v_mov_b32_e32 v92, v82
	v_mov_b32_e32 v93, v82
	v_mov_b32_e32 v94, v82
	v_mov_b32_e32 v95, v82
	v_mov_b32_e32 v96, v82
	v_mov_b32_e32 v97, v82
	v_mov_b64_e32 v[34:35], v[82:83]
	v_pk_mul_f32 v[24:25], v[24:25], v[50:51]
	v_pk_mul_f32 v[8:9], v[8:9], v[50:51]
	v_mov_b32_e32 v112, v82
	v_mov_b32_e32 v111, v82
	v_mov_b32_e32 v110, v82
	v_mov_b32_e32 v109, v82
	v_mov_b32_e32 v108, v82
	v_mov_b32_e32 v107, v82
	v_mov_b32_e32 v106, v82
	v_mov_b32_e32 v105, v82
	v_mov_b32_e32 v104, v82
	v_mov_b32_e32 v103, v82
	v_mov_b32_e32 v102, v82
	v_mov_b32_e32 v101, v82
	v_mov_b32_e32 v100, v82
	v_mov_b32_e32 v99, v82
	v_mov_b32_e32 v98, v82
	v_mov_b64_e32 v[36:37], v[84:85]
	v_mov_b64_e32 v[38:39], v[86:87]
	v_mov_b64_e32 v[40:41], v[88:89]
	v_mov_b64_e32 v[42:43], v[90:91]
	v_mov_b64_e32 v[44:45], v[92:93]
	v_mov_b64_e32 v[46:47], v[94:95]
	v_mov_b64_e32 v[48:49], v[96:97]
